# PEER apply U sweep made region-major (experts visited in four id ranges by all waves together, dynamic 8-slot row stream) so one quarter of the U table stays L2-resident
# speedup vs baseline: 1.1543x; 1.0235x over previous
; #define TIDX tid_fn()
; __device__ __forceinline__ void ph_peer_apply(const Params& P, int layer, float* xlat, float* xctx_in, float* xctx_out, int nrows, bool write_next, char* smem, float* xlat_out = nullptr) {
;     ...
;   const int tid = TIDX, wave = tid >> 6, lane = tid & 63;
;   const bool lact = lane < P6_NB;
;   const int lb = lact ? lane : 0;
;   for (int row = blockIdx.x * (NTHR / 64) + wave; row < nrows; row += gridDim.x * (NTHR / 64)) {
;     float xv[32];
; #pragma unroll
;     for (int j8 = 0; j8 < 4; ++j8) {
;       const h16x8 t = *(const h16x8*)(xq + (size_t)row * D + lb * 32 + j8 * 8);
; #pragma unroll
;       for (int j = 0; j < 8; ++j) xv[j8 * 8 + j] = lact ? (float)t[j] : 0.f;
;     }
;     const int id0 = seli[(size_t)row * NSEL + lane], id1 = seli[(size_t)row * NSEL + 64 + lane];
;     const float g0 = selg[(size_t)row * NSEL + lane], g1 = selg[(size_t)row * NSEL + 64 + lane];
;     float a0 = 0.f, a1 = 0.f;
;     P6Blk bufA[PB_G], bufB[PB_G];
.LBB0_1953:
	s_or_b64 exec, exec, s[6:7]
	s_mov_b64 s[4:5], s[96:97]
	s_waitcnt lgkmcnt(0)
	v_mov_b32_e32 v1, v0
	s_barrier
	s_load_dwordx4 s[4:7], s[96:97], 0x170
	s_load_dwordx4 s[8:11], s[96:97], 0x30
	v_readfirstlane_b32 s12, v0
	s_lshr_b32 s12, s12, 6
	v_and_b32_e32 v1, 63, v0
	v_mul_u32_u24_e32 v2, 24, v1
	v_add_u32_e32 v3, 0x600, v1
	v_lshlrev_b32_e32 v224, 6, v1
	v_lshlrev_b32_e32 v225, 7, v1
	v_lshlrev_b32_e32 v226, 2, v1
	v_lshrrev_b32_e32 v192, 2, v1
	v_and_b32_e32 v193, 1, v1
	v_lshl_add_u32 v192, v192, 1, v193
	v_lshlrev_b32_e32 v227, 2, v192
	s_mul_i32 s15, s12, 0x2800
	v_add_u32_e32 v228, s15, v226
	v_add_u32_e32 v227, s15, v227
	s_mov_b32 s46, 0x3333
	s_mov_b32 s47, 0
	s_mov_b32 s34, 0x22222222
	s_mov_b32 s35, 0x22222222
	s_waitcnt lgkmcnt(0)
	s_mov_b64 s[40:41], s[4:5]
	s_mov_b64 s[4:5], s[6:7]
	s_mov_b64 s[6:7], s[40:41]
	s_add_u32 s16, s4, 0x3c7c000
	s_addc_u32 s17, s5, 0
	s_add_u32 s18, s4, 0x7c7c000
	s_addc_u32 s19, s5, 0
	s_add_u32 s13, s60, s12
	s_lshl_b32 s44, s84, 3
	s_mov_b32 s50, 0
	s_mov_b32 s1, s13
.Lap0_ntl:
	s_add_u32 s50, s50, 1
	s_add_u32 s1, s1, s44
	s_cmp_lt_u32 s1, 0x8200
	s_cbranch_scc1 .Lap0_ntl
	s_mov_b32 s58, 0
	s_mov_b32 s59, 0
	s_mov_b32 s62, 0
	s_mov_b32 s48, 0
	s_mov_b32 s49, 0
	s_mov_b32 s45, s13
	s_lshl_b32 s15, s45, 12
	s_lshr_b32 s31, s45, 20
	s_add_u32 s20, s4, 0xbe4c000
	s_addc_u32 s21, s5, 0
	s_add_u32 s20, s20, s15
	s_addc_u32 s21, s21, s31
	s_lshl_b32 s15, s45, 9
	s_add_u32 s22, s4, 0x1404c000
	s_addc_u32 s23, s5, 0
	s_add_u32 s22, s22, s15
	s_addc_u32 s23, s23, 0
	global_load_dwordx4 v[4:7], v224, s[20:21]
	global_load_dwordx4 v[8:11], v224, s[20:21] offset:16
	global_load_dwordx4 v[12:15], v224, s[20:21] offset:32
	global_load_dwordx4 v[16:19], v224, s[20:21] offset:48
	global_load_dword v36, v226, s[22:23]
	global_load_dword v37, v226, s[22:23] offset:256
	s_waitcnt vmcnt(0)
	v_lshrrev_b32_e32 v195, 12, v36
	v_lshrrev_b32_e32 v196, 12, v37
	v_cmp_eq_u32_e64 s[52:53], s58, v195
	v_cmp_eq_u32_e64 s[54:55], s58, v196
	v_mov_b32_e32 v44, v36
	s_mov_b32 s61, 0
	s_mov_b32 s57, 0
	s_lshl_b32 s63, s59, 9
	s_mul_i32 s1, s12, 0x2800
	s_add_u32 s63, s63, s1
	s_lshl_b32 s1, s62, 31
	s_or_b32 s63, s63, s1
	v_mov_b32_e32 v45, 0
.Lap0_issp0:
	s_cmp_lg_u64 s[52:53], 0
	s_cbranch_scc0 .Lap0_slowp0
	s_ff1_i32_b64 s56, s[52:53]
	s_bitset0_b64 s[52:53], s56
	v_readlane_b32 s29, v44, s56
	s_add_u32 s57, s57, 1
	s_lshl_b32 s1, s56, 2
	s_add_u32 s33, s63, s1
.Lap0_ldp0:
	s_mul_hi_u32 s27, s29, 0x640
	s_mul_i32 s26, s29, 0x640
	s_add_u32 s26, s16, s26
	s_addc_u32 s27, s17, s27
	global_load_dwordx4 v[48:51], v2, s[26:27]
	global_load_dwordx2 v[52:53], v2, s[26:27] offset:16
	global_load_ubyte v54, v3, s[26:27]
	s_cmp_eq_u32 s57, 8
	s_cbranch_scc1 .Lap0_pfp0
.Lap0_aftp0:
.Lap0_issp1:
	s_cmp_lg_u64 s[52:53], 0
	s_cbranch_scc0 .Lap0_slowp1
	s_ff1_i32_b64 s56, s[52:53]
	s_bitset0_b64 s[52:53], s56
	v_readlane_b32 s29, v44, s56
	s_add_u32 s57, s57, 1
	s_lshl_b32 s1, s56, 2
	s_add_u32 s38, s63, s1
.Lap0_ldp1:
	s_mul_hi_u32 s27, s29, 0x640
	s_mul_i32 s26, s29, 0x640
	s_add_u32 s26, s16, s26
	s_addc_u32 s27, s17, s27
	global_load_dwordx4 v[56:59], v2, s[26:27]
	global_load_dwordx2 v[60:61], v2, s[26:27] offset:16
	global_load_ubyte v62, v3, s[26:27]
	s_cmp_eq_u32 s57, 8
	s_cbranch_scc1 .Lap0_pfp1
.Lap0_aftp1:
.Lap0_issp2:
	s_cmp_lg_u64 s[52:53], 0
	s_cbranch_scc0 .Lap0_slowp2
	s_ff1_i32_b64 s56, s[52:53]
	s_bitset0_b64 s[52:53], s56
	v_readlane_b32 s29, v44, s56
	s_add_u32 s57, s57, 1
	s_lshl_b32 s1, s56, 2
	s_add_u32 s39, s63, s1
.Lap0_ldp2:
	s_mul_hi_u32 s27, s29, 0x640
	s_mul_i32 s26, s29, 0x640
	s_add_u32 s26, s16, s26
	s_addc_u32 s27, s17, s27
	global_load_dwordx4 v[64:67], v2, s[26:27]
	global_load_dwordx2 v[68:69], v2, s[26:27] offset:16
	global_load_ubyte v70, v3, s[26:27]
	s_cmp_eq_u32 s57, 8
	s_cbranch_scc1 .Lap0_pfp2
.Lap0_aftp2:
.Lap0_issp3:
	s_cmp_lg_u64 s[52:53], 0
	s_cbranch_scc0 .Lap0_slowp3
	s_ff1_i32_b64 s56, s[52:53]
	s_bitset0_b64 s[52:53], s56
	v_readlane_b32 s29, v44, s56
	s_add_u32 s57, s57, 1
	s_lshl_b32 s1, s56, 2
	s_add_u32 s51, s63, s1
.Lap0_ldp3:
	s_mul_hi_u32 s27, s29, 0x640
	s_mul_i32 s26, s29, 0x640
	s_add_u32 s26, s16, s26
	s_addc_u32 s27, s17, s27
	global_load_dwordx4 v[72:75], v2, s[26:27]
	global_load_dwordx2 v[76:77], v2, s[26:27] offset:16
	global_load_ubyte v78, v3, s[26:27]
	s_cmp_eq_u32 s57, 8
	s_cbranch_scc1 .Lap0_pfp3
.Lap0_aftp3:
.Lap0_issp4:
	s_cmp_lg_u64 s[52:53], 0
	s_cbranch_scc0 .Lap0_slowp4
	s_ff1_i32_b64 s56, s[52:53]
	s_bitset0_b64 s[52:53], s56
	v_readlane_b32 s29, v44, s56
	s_add_u32 s57, s57, 1
	s_lshl_b32 s1, s56, 2
	s_add_u32 s28, s63, s1
.Lap0_ldp4:
	s_mul_hi_u32 s27, s29, 0x640
	s_mul_i32 s26, s29, 0x640
	s_add_u32 s26, s16, s26
	s_addc_u32 s27, s17, s27
	global_load_dwordx4 v[80:83], v2, s[26:27]
	global_load_dwordx2 v[84:85], v2, s[26:27] offset:16
	global_load_ubyte v86, v3, s[26:27]
	s_cmp_eq_u32 s57, 8
	s_cbranch_scc1 .Lap0_pfp4
.Lap0_aftp4:
.Lap0_issp5:
	s_cmp_lg_u64 s[52:53], 0
	s_cbranch_scc0 .Lap0_slowp5
	s_ff1_i32_b64 s56, s[52:53]
	s_bitset0_b64 s[52:53], s56
	v_readlane_b32 s29, v44, s56
	s_add_u32 s57, s57, 1
	s_lshl_b32 s1, s56, 2
	s_add_u32 s30, s63, s1
.Lap0_ldp5:
	s_mul_hi_u32 s27, s29, 0x640
	s_mul_i32 s26, s29, 0x640
	s_add_u32 s26, s16, s26
	s_addc_u32 s27, s17, s27
	global_load_dwordx4 v[88:91], v2, s[26:27]
	global_load_dwordx2 v[92:93], v2, s[26:27] offset:16
	global_load_ubyte v94, v3, s[26:27]
	s_cmp_eq_u32 s57, 8
	s_cbranch_scc1 .Lap0_pfp5
.Lap0_aftp5:
.Lap0_issp6:
	s_cmp_lg_u64 s[52:53], 0
	s_cbranch_scc0 .Lap0_slowp6
	s_ff1_i32_b64 s56, s[52:53]
	s_bitset0_b64 s[52:53], s56
	v_readlane_b32 s29, v44, s56
	s_add_u32 s57, s57, 1
	s_lshl_b32 s1, s56, 2
	s_add_u32 s36, s63, s1
.Lap0_ldp6:
	s_mul_hi_u32 s27, s29, 0x640
	s_mul_i32 s26, s29, 0x640
	s_add_u32 s26, s16, s26
	s_addc_u32 s27, s17, s27
	global_load_dwordx4 v[96:99], v2, s[26:27]
	global_load_dwordx2 v[100:101], v2, s[26:27] offset:16
	global_load_ubyte v102, v3, s[26:27]
	s_cmp_eq_u32 s57, 8
	s_cbranch_scc1 .Lap0_pfp6
.Lap0_aftp6:
.Lap0_issp7:
	s_cmp_lg_u64 s[52:53], 0
	s_cbranch_scc0 .Lap0_slowp7
	s_ff1_i32_b64 s56, s[52:53]
	s_bitset0_b64 s[52:53], s56
	v_readlane_b32 s29, v44, s56
	s_add_u32 s57, s57, 1
	s_lshl_b32 s1, s56, 2
	s_add_u32 s37, s63, s1
.Lap0_ldp7:
	s_mul_hi_u32 s27, s29, 0x640
	s_mul_i32 s26, s29, 0x640
	s_add_u32 s26, s16, s26
	s_addc_u32 s27, s17, s27
	global_load_dwordx4 v[104:107], v2, s[26:27]
	global_load_dwordx2 v[108:109], v2, s[26:27] offset:16
	global_load_ubyte v110, v3, s[26:27]
	s_cmp_eq_u32 s57, 8
	s_cbranch_scc1 .Lap0_pfp7
.Lap0_aftp7:
	s_branch .Lap0_pass
.Lap0_slowp0:
	s_mov_b32 s0, 0
	s_branch .Lap0_slowcp

.Lap0_slowp1:
	s_mov_b32 s0, 1
	s_branch .Lap0_slowcp

.Lap0_slowp2:
	s_mov_b32 s0, 2
	s_branch .Lap0_slowcp

.Lap0_slowp3:
	s_mov_b32 s0, 3
	s_branch .Lap0_slowcp

.Lap0_slowp4:
	s_mov_b32 s0, 4
	s_branch .Lap0_slowcp

.Lap0_slowp5:
	s_mov_b32 s0, 5
	s_branch .Lap0_slowcp

.Lap0_slowp6:
	s_mov_b32 s0, 6
	s_branch .Lap0_slowcp

.Lap0_slowp7:
	s_mov_b32 s0, 7
	s_branch .Lap0_slowcp

; __device__ __forceinline__ void ph_peer_apply(const Params& P, int layer, float* xlat, float* xctx_in, float* xctx_out, int nrows, bool write_next, char* smem, float* xlat_out = nullptr) {
;     ...
;   for (int row = blockIdx.x * (NTHR / 64) + wave; row < nrows; row += gridDim.x * (NTHR / 64)) {
;     float xv[32];
; #pragma unroll
;     for (int j8 = 0; j8 < 4; ++j8) {
;       const h16x8 t = *(const h16x8*)(xq + (size_t)row * D + lb * 32 + j8 * 8);
; #pragma unroll
;       for (int j = 0; j < 8; ++j) xv[j8 * 8 + j] = lact ? (float)t[j] : 0.f;
;     }
;     const int id0 = seli[(size_t)row * NSEL + lane], id1 = seli[(size_t)row * NSEL + 64 + lane];
;     const float g0 = selg[(size_t)row * NSEL + lane], g1 = selg[(size_t)row * NSEL + 64 + lane];
;     float a0 = 0.f, a1 = 0.f;
;     P6Blk bufA[PB_G], bufB[PB_G];
.Lap0_slowcp:
	s_cmp_lg_u32 s61, 0
	s_cbranch_scc1 .Lap0_h1p
	s_mov_b32 s61, 1
	s_mov_b64 s[52:53], s[54:55]
	v_mov_b32_e32 v44, v37
	s_add_u32 s63, s63, 0x100
	s_branch .Lap0_redop
.Lap0_h1p:
	s_cmp_lt_u32 s57, 8
	s_cbranch_scc1 .Lap0_dummyp
	s_cmp_lg_u32 s48, 0
	s_cbranch_scc1 .Lap0_dummyp
	s_add_u32 s59, s59, 1
	s_cmp_lt_u32 s59, s50
	s_cbranch_scc1 .Lap0_advp
	s_mov_b32 s59, 0
	s_add_u32 s58, s58, 1
	s_cmp_lt_u32 s58, 4
	s_cbranch_scc1 .Lap0_advp
	s_mov_b32 s48, 1
	s_branch .Lap0_dummyp
.Lap0_advp:
	s_cmp_lt_u32 s57, 15
	s_cbranch_scc0 .Lap0_advwp
	s_waitcnt vmcnt(0)
.Lap0_advwp:
	s_waitcnt vmcnt(21)
	v_mov_b32_e32 v36, v38
	v_mov_b32_e32 v37, v39
	s_xor_b32 s62, s62, 1
	v_lshrrev_b32_e32 v195, 12, v36
	v_lshrrev_b32_e32 v196, 12, v37
	v_cmp_eq_u32_e64 s[52:53], s58, v195
	v_cmp_eq_u32_e64 s[54:55], s58, v196
	v_mov_b32_e32 v44, v36
	s_mov_b32 s61, 0
	s_mov_b32 s57, 0
	s_lshl_b32 s63, s59, 9
	s_mul_i32 s1, s12, 0x2800
	s_add_u32 s63, s63, s1
	s_lshl_b32 s1, s62, 31
	s_or_b32 s63, s63, s1
.Lap0_redop:
	s_cmp_eq_u32 s0, 0
	s_cbranch_scc1 .Lap0_issp0
	s_cmp_eq_u32 s0, 1
	s_cbranch_scc1 .Lap0_issp1
	s_cmp_eq_u32 s0, 2
	s_cbranch_scc1 .Lap0_issp2
	s_cmp_eq_u32 s0, 3
	s_cbranch_scc1 .Lap0_issp3
	s_cmp_eq_u32 s0, 4
	s_cbranch_scc1 .Lap0_issp4
	s_cmp_eq_u32 s0, 5
	s_cbranch_scc1 .Lap0_issp5
	s_cmp_eq_u32 s0, 6
	s_cbranch_scc1 .Lap0_issp6
	s_cmp_eq_u32 s0, 7
	s_cbranch_scc1 .Lap0_issp7
	s_branch .Lap0_issp0
.Lap0_dummyp:
	s_add_u32 s57, s57, 1
	s_mov_b32 s29, 0
	s_mul_i32 s1, s12, 0x2800
	s_add_u32 s1, s1, 9216
	s_lshl_b32 s15, s62, 31
	s_or_b32 s1, s1, s15
	s_cmp_eq_u32 s0, 0
	s_cselect_b32 s33, s1, s33
	s_cmp_eq_u32 s0, 1
	s_cselect_b32 s38, s1, s38
	s_cmp_eq_u32 s0, 2
	s_cselect_b32 s39, s1, s39
	s_cmp_eq_u32 s0, 3
	s_cselect_b32 s51, s1, s51
	s_cmp_eq_u32 s0, 4
	s_cselect_b32 s28, s1, s28
	s_cmp_eq_u32 s0, 5
	s_cselect_b32 s30, s1, s30
	s_cmp_eq_u32 s0, 6
	s_cselect_b32 s36, s1, s36
	s_cmp_eq_u32 s0, 7
	s_cselect_b32 s37, s1, s37
	s_cmp_eq_u32 s0, 0
	s_cbranch_scc1 .Lap0_ldp0
	s_cmp_eq_u32 s0, 1
	s_cbranch_scc1 .Lap0_ldp1
	s_cmp_eq_u32 s0, 2
	s_cbranch_scc1 .Lap0_ldp2
	s_cmp_eq_u32 s0, 3
	s_cbranch_scc1 .Lap0_ldp3
	s_cmp_eq_u32 s0, 4
	s_cbranch_scc1 .Lap0_ldp4
	s_cmp_eq_u32 s0, 5
	s_cbranch_scc1 .Lap0_ldp5
	s_cmp_eq_u32 s0, 6
	s_cbranch_scc1 .Lap0_ldp6
	s_cmp_eq_u32 s0, 7
	s_cbranch_scc1 .Lap0_ldp7
	s_branch .Lap0_ldp0
.Lap0_pfcp:
	s_add_u32 s1, s59, 1
	s_cmp_lt_u32 s1, s50
	s_cbranch_scc1 .Lap0_pfkp
	s_mov_b32 s1, 0
	s_cmp_lt_u32 s58, 3
	s_cbranch_scc0 .Lap0_pfretp
.Lap0_pfkp:
	s_mul_i32 s1, s1, s44
	s_add_u32 s1, s1, s13
	s_lshl_b32 s15, s1, 12
	s_lshr_b32 s31, s1, 20
	s_add_u32 s20, s4, 0xbe4c000
	s_addc_u32 s21, s5, 0
	s_add_u32 s20, s20, s15
	s_addc_u32 s21, s21, s31
	s_lshl_b32 s15, s1, 9
	s_add_u32 s22, s4, 0x1404c000
	s_addc_u32 s23, s5, 0
	s_add_u32 s22, s22, s15
	s_addc_u32 s23, s23, 0
	global_load_dword v38, v226, s[22:23]
	global_load_dword v39, v226, s[22:23] offset:256
	s_cmp_lg_u32 s62, 0
	s_cbranch_scc1 .Lap0_pfx0p
	global_load_dwordx4 v[20:23], v224, s[20:21]
	global_load_dwordx4 v[24:27], v224, s[20:21] offset:16
	global_load_dwordx4 v[28:31], v224, s[20:21] offset:32
	global_load_dwordx4 v[32:35], v224, s[20:21] offset:48
	s_branch .Lap0_pfretp
.Lap0_pfx0p:
	global_load_dwordx4 v[4:7], v224, s[20:21]
	global_load_dwordx4 v[8:11], v224, s[20:21] offset:16
	global_load_dwordx4 v[12:15], v224, s[20:21] offset:32
	global_load_dwordx4 v[16:19], v224, s[20:21] offset:48

.Lap0_pass:
	s_waitcnt vmcnt(21)
	v_lshlrev_b32_e32 v192, 23, v54
	v_cvt_scalef32_pk32_f32_fp6 v[112:143], v[48:53], v192
	s_bitcmp1_b32 s33, 31
	s_cbranch_scc1 .Lap0_cB0
	v_fma_mix_f32 v144, v112, v4, 0 op_sel_hi:[0,1,0]
	v_fma_mix_f32 v145, v113, v4, 0 op_sel:[0,1,0] op_sel_hi:[0,1,0]
	v_fma_mix_f32 v144, v114, v5, v144 op_sel_hi:[0,1,0]
	v_fma_mix_f32 v145, v115, v5, v145 op_sel:[0,1,0] op_sel_hi:[0,1,0]
	v_fma_mix_f32 v144, v116, v6, v144 op_sel_hi:[0,1,0]
	v_fma_mix_f32 v145, v117, v6, v145 op_sel:[0,1,0] op_sel_hi:[0,1,0]
	v_fma_mix_f32 v144, v118, v7, v144 op_sel_hi:[0,1,0]
	v_fma_mix_f32 v145, v119, v7, v145 op_sel:[0,1,0] op_sel_hi:[0,1,0]
	v_fma_mix_f32 v144, v120, v8, v144 op_sel_hi:[0,1,0]
	v_fma_mix_f32 v145, v121, v8, v145 op_sel:[0,1,0] op_sel_hi:[0,1,0]
	v_fma_mix_f32 v144, v122, v9, v144 op_sel_hi:[0,1,0]
	v_fma_mix_f32 v145, v123, v9, v145 op_sel:[0,1,0] op_sel_hi:[0,1,0]
	v_fma_mix_f32 v144, v124, v10, v144 op_sel_hi:[0,1,0]
	v_fma_mix_f32 v145, v125, v10, v145 op_sel:[0,1,0] op_sel_hi:[0,1,0]
	v_fma_mix_f32 v144, v126, v11, v144 op_sel_hi:[0,1,0]
	v_fma_mix_f32 v145, v127, v11, v145 op_sel:[0,1,0] op_sel_hi:[0,1,0]
	v_fma_mix_f32 v144, v128, v12, v144 op_sel_hi:[0,1,0]
	v_fma_mix_f32 v145, v129, v12, v145 op_sel:[0,1,0] op_sel_hi:[0,1,0]
	v_fma_mix_f32 v144, v130, v13, v144 op_sel_hi:[0,1,0]
	v_fma_mix_f32 v145, v131, v13, v145 op_sel:[0,1,0] op_sel_hi:[0,1,0]
	v_fma_mix_f32 v144, v132, v14, v144 op_sel_hi:[0,1,0]
	v_fma_mix_f32 v145, v133, v14, v145 op_sel:[0,1,0] op_sel_hi:[0,1,0]
	v_fma_mix_f32 v144, v134, v15, v144 op_sel_hi:[0,1,0]
	v_fma_mix_f32 v145, v135, v15, v145 op_sel:[0,1,0] op_sel_hi:[0,1,0]
	v_fma_mix_f32 v144, v136, v16, v144 op_sel_hi:[0,1,0]
	v_fma_mix_f32 v145, v137, v16, v145 op_sel:[0,1,0] op_sel_hi:[0,1,0]
	v_fma_mix_f32 v144, v138, v17, v144 op_sel_hi:[0,1,0]
	v_fma_mix_f32 v145, v139, v17, v145 op_sel:[0,1,0] op_sel_hi:[0,1,0]
	v_fma_mix_f32 v144, v140, v18, v144 op_sel_hi:[0,1,0]
	v_fma_mix_f32 v145, v141, v18, v145 op_sel:[0,1,0] op_sel_hi:[0,1,0]
	v_fma_mix_f32 v144, v142, v19, v144 op_sel_hi:[0,1,0]
	v_fma_mix_f32 v145, v143, v19, v145 op_sel:[0,1,0] op_sel_hi:[0,1,0]
	v_add_f32_e32 v146, v144, v145
	s_branch .Lap0_cD0
.Lap0_cB0:
	v_fma_mix_f32 v144, v112, v20, 0 op_sel_hi:[0,1,0]
	v_fma_mix_f32 v145, v113, v20, 0 op_sel:[0,1,0] op_sel_hi:[0,1,0]
	v_fma_mix_f32 v144, v114, v21, v144 op_sel_hi:[0,1,0]
	v_fma_mix_f32 v145, v115, v21, v145 op_sel:[0,1,0] op_sel_hi:[0,1,0]
	v_fma_mix_f32 v144, v116, v22, v144 op_sel_hi:[0,1,0]
	v_fma_mix_f32 v145, v117, v22, v145 op_sel:[0,1,0] op_sel_hi:[0,1,0]
	v_fma_mix_f32 v144, v118, v23, v144 op_sel_hi:[0,1,0]
	v_fma_mix_f32 v145, v119, v23, v145 op_sel:[0,1,0] op_sel_hi:[0,1,0]
	v_fma_mix_f32 v144, v120, v24, v144 op_sel_hi:[0,1,0]
	v_fma_mix_f32 v145, v121, v24, v145 op_sel:[0,1,0] op_sel_hi:[0,1,0]
	v_fma_mix_f32 v144, v122, v25, v144 op_sel_hi:[0,1,0]
	v_fma_mix_f32 v145, v123, v25, v145 op_sel:[0,1,0] op_sel_hi:[0,1,0]
	v_fma_mix_f32 v144, v124, v26, v144 op_sel_hi:[0,1,0]
	v_fma_mix_f32 v145, v125, v26, v145 op_sel:[0,1,0] op_sel_hi:[0,1,0]
	v_fma_mix_f32 v144, v126, v27, v144 op_sel_hi:[0,1,0]
	v_fma_mix_f32 v145, v127, v27, v145 op_sel:[0,1,0] op_sel_hi:[0,1,0]
	v_fma_mix_f32 v144, v128, v28, v144 op_sel_hi:[0,1,0]
	v_fma_mix_f32 v145, v129, v28, v145 op_sel:[0,1,0] op_sel_hi:[0,1,0]
	v_fma_mix_f32 v144, v130, v29, v144 op_sel_hi:[0,1,0]
	v_fma_mix_f32 v145, v131, v29, v145 op_sel:[0,1,0] op_sel_hi:[0,1,0]
	v_fma_mix_f32 v144, v132, v30, v144 op_sel_hi:[0,1,0]
	v_fma_mix_f32 v145, v133, v30, v145 op_sel:[0,1,0] op_sel_hi:[0,1,0]
	v_fma_mix_f32 v144, v134, v31, v144 op_sel_hi:[0,1,0]
	v_fma_mix_f32 v145, v135, v31, v145 op_sel:[0,1,0] op_sel_hi:[0,1,0]
	v_fma_mix_f32 v144, v136, v32, v144 op_sel_hi:[0,1,0]
	v_fma_mix_f32 v145, v137, v32, v145 op_sel:[0,1,0] op_sel_hi:[0,1,0]
	v_fma_mix_f32 v144, v138, v33, v144 op_sel_hi:[0,1,0]
	v_fma_mix_f32 v145, v139, v33, v145 op_sel:[0,1,0] op_sel_hi:[0,1,0]
	v_fma_mix_f32 v144, v140, v34, v144 op_sel_hi:[0,1,0]
	v_fma_mix_f32 v145, v141, v34, v145 op_sel:[0,1,0] op_sel_hi:[0,1,0]
	v_fma_mix_f32 v144, v142, v35, v144 op_sel_hi:[0,1,0]
	v_fma_mix_f32 v145, v143, v35, v145 op_sel:[0,1,0] op_sel_hi:[0,1,0]
	v_add_f32_e32 v146, v144, v145
.Lap0_cD0:
	s_bitset0_b32 s33, 31
	v_writelane_b32 v45, s33, 0

.Lap0_aftl0:
	s_waitcnt vmcnt(21)
	v_lshlrev_b32_e32 v192, 23, v62
	v_cvt_scalef32_pk32_f32_fp6 v[112:143], v[56:61], v192
	s_bitcmp1_b32 s38, 31
	s_cbranch_scc1 .Lap0_cB1
	v_fma_mix_f32 v144, v112, v4, 0 op_sel_hi:[0,1,0]
	v_fma_mix_f32 v145, v113, v4, 0 op_sel:[0,1,0] op_sel_hi:[0,1,0]
	v_fma_mix_f32 v144, v114, v5, v144 op_sel_hi:[0,1,0]
	v_fma_mix_f32 v145, v115, v5, v145 op_sel:[0,1,0] op_sel_hi:[0,1,0]
	v_fma_mix_f32 v144, v116, v6, v144 op_sel_hi:[0,1,0]
	v_fma_mix_f32 v145, v117, v6, v145 op_sel:[0,1,0] op_sel_hi:[0,1,0]
	v_fma_mix_f32 v144, v118, v7, v144 op_sel_hi:[0,1,0]
	v_fma_mix_f32 v145, v119, v7, v145 op_sel:[0,1,0] op_sel_hi:[0,1,0]
	v_fma_mix_f32 v144, v120, v8, v144 op_sel_hi:[0,1,0]
	v_fma_mix_f32 v145, v121, v8, v145 op_sel:[0,1,0] op_sel_hi:[0,1,0]
	v_fma_mix_f32 v144, v122, v9, v144 op_sel_hi:[0,1,0]
	v_fma_mix_f32 v145, v123, v9, v145 op_sel:[0,1,0] op_sel_hi:[0,1,0]
	v_fma_mix_f32 v144, v124, v10, v144 op_sel_hi:[0,1,0]
	v_fma_mix_f32 v145, v125, v10, v145 op_sel:[0,1,0] op_sel_hi:[0,1,0]
	v_fma_mix_f32 v144, v126, v11, v144 op_sel_hi:[0,1,0]
	v_fma_mix_f32 v145, v127, v11, v145 op_sel:[0,1,0] op_sel_hi:[0,1,0]
	v_fma_mix_f32 v144, v128, v12, v144 op_sel_hi:[0,1,0]
	v_fma_mix_f32 v145, v129, v12, v145 op_sel:[0,1,0] op_sel_hi:[0,1,0]
	v_fma_mix_f32 v144, v130, v13, v144 op_sel_hi:[0,1,0]
	v_fma_mix_f32 v145, v131, v13, v145 op_sel:[0,1,0] op_sel_hi:[0,1,0]
	v_fma_mix_f32 v144, v132, v14, v144 op_sel_hi:[0,1,0]
	v_fma_mix_f32 v145, v133, v14, v145 op_sel:[0,1,0] op_sel_hi:[0,1,0]
	v_fma_mix_f32 v144, v134, v15, v144 op_sel_hi:[0,1,0]
	v_fma_mix_f32 v145, v135, v15, v145 op_sel:[0,1,0] op_sel_hi:[0,1,0]
	v_fma_mix_f32 v144, v136, v16, v144 op_sel_hi:[0,1,0]
	v_fma_mix_f32 v145, v137, v16, v145 op_sel:[0,1,0] op_sel_hi:[0,1,0]
	v_fma_mix_f32 v144, v138, v17, v144 op_sel_hi:[0,1,0]
	v_fma_mix_f32 v145, v139, v17, v145 op_sel:[0,1,0] op_sel_hi:[0,1,0]
	v_fma_mix_f32 v144, v140, v18, v144 op_sel_hi:[0,1,0]
	v_fma_mix_f32 v145, v141, v18, v145 op_sel:[0,1,0] op_sel_hi:[0,1,0]
	v_fma_mix_f32 v144, v142, v19, v144 op_sel_hi:[0,1,0]
	v_fma_mix_f32 v145, v143, v19, v145 op_sel:[0,1,0] op_sel_hi:[0,1,0]
	v_add_f32_e32 v147, v144, v145
	s_branch .Lap0_cD1
.Lap0_cB1:
	v_fma_mix_f32 v144, v112, v20, 0 op_sel_hi:[0,1,0]
	v_fma_mix_f32 v145, v113, v20, 0 op_sel:[0,1,0] op_sel_hi:[0,1,0]
	v_fma_mix_f32 v144, v114, v21, v144 op_sel_hi:[0,1,0]
	v_fma_mix_f32 v145, v115, v21, v145 op_sel:[0,1,0] op_sel_hi:[0,1,0]
	v_fma_mix_f32 v144, v116, v22, v144 op_sel_hi:[0,1,0]
	v_fma_mix_f32 v145, v117, v22, v145 op_sel:[0,1,0] op_sel_hi:[0,1,0]
	v_fma_mix_f32 v144, v118, v23, v144 op_sel_hi:[0,1,0]
	v_fma_mix_f32 v145, v119, v23, v145 op_sel:[0,1,0] op_sel_hi:[0,1,0]
	v_fma_mix_f32 v144, v120, v24, v144 op_sel_hi:[0,1,0]
	v_fma_mix_f32 v145, v121, v24, v145 op_sel:[0,1,0] op_sel_hi:[0,1,0]
	v_fma_mix_f32 v144, v122, v25, v144 op_sel_hi:[0,1,0]
	v_fma_mix_f32 v145, v123, v25, v145 op_sel:[0,1,0] op_sel_hi:[0,1,0]
	v_fma_mix_f32 v144, v124, v26, v144 op_sel_hi:[0,1,0]
	v_fma_mix_f32 v145, v125, v26, v145 op_sel:[0,1,0] op_sel_hi:[0,1,0]
	v_fma_mix_f32 v144, v126, v27, v144 op_sel_hi:[0,1,0]
	v_fma_mix_f32 v145, v127, v27, v145 op_sel:[0,1,0] op_sel_hi:[0,1,0]
	v_fma_mix_f32 v144, v128, v28, v144 op_sel_hi:[0,1,0]
	v_fma_mix_f32 v145, v129, v28, v145 op_sel:[0,1,0] op_sel_hi:[0,1,0]
	v_fma_mix_f32 v144, v130, v29, v144 op_sel_hi:[0,1,0]
	v_fma_mix_f32 v145, v131, v29, v145 op_sel:[0,1,0] op_sel_hi:[0,1,0]
	v_fma_mix_f32 v144, v132, v30, v144 op_sel_hi:[0,1,0]
	v_fma_mix_f32 v145, v133, v30, v145 op_sel:[0,1,0] op_sel_hi:[0,1,0]
	v_fma_mix_f32 v144, v134, v31, v144 op_sel_hi:[0,1,0]
	v_fma_mix_f32 v145, v135, v31, v145 op_sel:[0,1,0] op_sel_hi:[0,1,0]
	v_fma_mix_f32 v144, v136, v32, v144 op_sel_hi:[0,1,0]
	v_fma_mix_f32 v145, v137, v32, v145 op_sel:[0,1,0] op_sel_hi:[0,1,0]
	v_fma_mix_f32 v144, v138, v33, v144 op_sel_hi:[0,1,0]
	v_fma_mix_f32 v145, v139, v33, v145 op_sel:[0,1,0] op_sel_hi:[0,1,0]
	v_fma_mix_f32 v144, v140, v34, v144 op_sel_hi:[0,1,0]
	v_fma_mix_f32 v145, v141, v34, v145 op_sel:[0,1,0] op_sel_hi:[0,1,0]
	v_fma_mix_f32 v144, v142, v35, v144 op_sel_hi:[0,1,0]
	v_fma_mix_f32 v145, v143, v35, v145 op_sel:[0,1,0] op_sel_hi:[0,1,0]
	v_add_f32_e32 v147, v144, v145
.Lap0_cD1:
	s_bitset0_b32 s38, 31
	v_writelane_b32 v45, s38, 1
.Lap0_issl1:
	s_cmp_lg_u64 s[52:53], 0
	s_cbranch_scc0 .Lap0_slowl1
	s_ff1_i32_b64 s56, s[52:53]
	s_bitset0_b64 s[52:53], s56
	v_readlane_b32 s29, v44, s56
	s_add_u32 s57, s57, 1
	s_lshl_b32 s1, s56, 2
	s_add_u32 s38, s63, s1

.Lap0_aftl1:
	s_waitcnt vmcnt(21)
	v_lshlrev_b32_e32 v192, 23, v70
	v_cvt_scalef32_pk32_f32_fp6 v[112:143], v[64:69], v192
	s_bitcmp1_b32 s39, 31
	s_cbranch_scc1 .Lap0_cB2
	v_fma_mix_f32 v144, v112, v4, 0 op_sel_hi:[0,1,0]
	v_fma_mix_f32 v145, v113, v4, 0 op_sel:[0,1,0] op_sel_hi:[0,1,0]
	v_fma_mix_f32 v144, v114, v5, v144 op_sel_hi:[0,1,0]
	v_fma_mix_f32 v145, v115, v5, v145 op_sel:[0,1,0] op_sel_hi:[0,1,0]
	v_fma_mix_f32 v144, v116, v6, v144 op_sel_hi:[0,1,0]
	v_fma_mix_f32 v145, v117, v6, v145 op_sel:[0,1,0] op_sel_hi:[0,1,0]
	v_fma_mix_f32 v144, v118, v7, v144 op_sel_hi:[0,1,0]
	v_fma_mix_f32 v145, v119, v7, v145 op_sel:[0,1,0] op_sel_hi:[0,1,0]
	v_fma_mix_f32 v144, v120, v8, v144 op_sel_hi:[0,1,0]
	v_fma_mix_f32 v145, v121, v8, v145 op_sel:[0,1,0] op_sel_hi:[0,1,0]
	v_fma_mix_f32 v144, v122, v9, v144 op_sel_hi:[0,1,0]
	v_fma_mix_f32 v145, v123, v9, v145 op_sel:[0,1,0] op_sel_hi:[0,1,0]
	v_fma_mix_f32 v144, v124, v10, v144 op_sel_hi:[0,1,0]
	v_fma_mix_f32 v145, v125, v10, v145 op_sel:[0,1,0] op_sel_hi:[0,1,0]
	v_fma_mix_f32 v144, v126, v11, v144 op_sel_hi:[0,1,0]
	v_fma_mix_f32 v145, v127, v11, v145 op_sel:[0,1,0] op_sel_hi:[0,1,0]
	v_fma_mix_f32 v144, v128, v12, v144 op_sel_hi:[0,1,0]
	v_fma_mix_f32 v145, v129, v12, v145 op_sel:[0,1,0] op_sel_hi:[0,1,0]
	v_fma_mix_f32 v144, v130, v13, v144 op_sel_hi:[0,1,0]
	v_fma_mix_f32 v145, v131, v13, v145 op_sel:[0,1,0] op_sel_hi:[0,1,0]
	v_fma_mix_f32 v144, v132, v14, v144 op_sel_hi:[0,1,0]
	v_fma_mix_f32 v145, v133, v14, v145 op_sel:[0,1,0] op_sel_hi:[0,1,0]
	v_fma_mix_f32 v144, v134, v15, v144 op_sel_hi:[0,1,0]
	v_fma_mix_f32 v145, v135, v15, v145 op_sel:[0,1,0] op_sel_hi:[0,1,0]
	v_fma_mix_f32 v144, v136, v16, v144 op_sel_hi:[0,1,0]
	v_fma_mix_f32 v145, v137, v16, v145 op_sel:[0,1,0] op_sel_hi:[0,1,0]
	v_fma_mix_f32 v144, v138, v17, v144 op_sel_hi:[0,1,0]
	v_fma_mix_f32 v145, v139, v17, v145 op_sel:[0,1,0] op_sel_hi:[0,1,0]
	v_fma_mix_f32 v144, v140, v18, v144 op_sel_hi:[0,1,0]
	v_fma_mix_f32 v145, v141, v18, v145 op_sel:[0,1,0] op_sel_hi:[0,1,0]
	v_fma_mix_f32 v144, v142, v19, v144 op_sel_hi:[0,1,0]
	v_fma_mix_f32 v145, v143, v19, v145 op_sel:[0,1,0] op_sel_hi:[0,1,0]
	v_add_f32_e32 v148, v144, v145
	s_branch .Lap0_cD2
.Lap0_cB2:
	v_fma_mix_f32 v144, v112, v20, 0 op_sel_hi:[0,1,0]
	v_fma_mix_f32 v145, v113, v20, 0 op_sel:[0,1,0] op_sel_hi:[0,1,0]
	v_fma_mix_f32 v144, v114, v21, v144 op_sel_hi:[0,1,0]
	v_fma_mix_f32 v145, v115, v21, v145 op_sel:[0,1,0] op_sel_hi:[0,1,0]
	v_fma_mix_f32 v144, v116, v22, v144 op_sel_hi:[0,1,0]
	v_fma_mix_f32 v145, v117, v22, v145 op_sel:[0,1,0] op_sel_hi:[0,1,0]
	v_fma_mix_f32 v144, v118, v23, v144 op_sel_hi:[0,1,0]
	v_fma_mix_f32 v145, v119, v23, v145 op_sel:[0,1,0] op_sel_hi:[0,1,0]
	v_fma_mix_f32 v144, v120, v24, v144 op_sel_hi:[0,1,0]
	v_fma_mix_f32 v145, v121, v24, v145 op_sel:[0,1,0] op_sel_hi:[0,1,0]
	v_fma_mix_f32 v144, v122, v25, v144 op_sel_hi:[0,1,0]
	v_fma_mix_f32 v145, v123, v25, v145 op_sel:[0,1,0] op_sel_hi:[0,1,0]
	v_fma_mix_f32 v144, v124, v26, v144 op_sel_hi:[0,1,0]
	v_fma_mix_f32 v145, v125, v26, v145 op_sel:[0,1,0] op_sel_hi:[0,1,0]
	v_fma_mix_f32 v144, v126, v27, v144 op_sel_hi:[0,1,0]
	v_fma_mix_f32 v145, v127, v27, v145 op_sel:[0,1,0] op_sel_hi:[0,1,0]
	v_fma_mix_f32 v144, v128, v28, v144 op_sel_hi:[0,1,0]
	v_fma_mix_f32 v145, v129, v28, v145 op_sel:[0,1,0] op_sel_hi:[0,1,0]
	v_fma_mix_f32 v144, v130, v29, v144 op_sel_hi:[0,1,0]
	v_fma_mix_f32 v145, v131, v29, v145 op_sel:[0,1,0] op_sel_hi:[0,1,0]
	v_fma_mix_f32 v144, v132, v30, v144 op_sel_hi:[0,1,0]
	v_fma_mix_f32 v145, v133, v30, v145 op_sel:[0,1,0] op_sel_hi:[0,1,0]
	v_fma_mix_f32 v144, v134, v31, v144 op_sel_hi:[0,1,0]
	v_fma_mix_f32 v145, v135, v31, v145 op_sel:[0,1,0] op_sel_hi:[0,1,0]
	v_fma_mix_f32 v144, v136, v32, v144 op_sel_hi:[0,1,0]
	v_fma_mix_f32 v145, v137, v32, v145 op_sel:[0,1,0] op_sel_hi:[0,1,0]
	v_fma_mix_f32 v144, v138, v33, v144 op_sel_hi:[0,1,0]
	v_fma_mix_f32 v145, v139, v33, v145 op_sel:[0,1,0] op_sel_hi:[0,1,0]
	v_fma_mix_f32 v144, v140, v34, v144 op_sel_hi:[0,1,0]
	v_fma_mix_f32 v145, v141, v34, v145 op_sel:[0,1,0] op_sel_hi:[0,1,0]
	v_fma_mix_f32 v144, v142, v35, v144 op_sel_hi:[0,1,0]
	v_fma_mix_f32 v145, v143, v35, v145 op_sel:[0,1,0] op_sel_hi:[0,1,0]
	v_add_f32_e32 v148, v144, v145
.Lap0_cD2:
	s_bitset0_b32 s39, 31
	v_writelane_b32 v45, s39, 4
.Lap0_issl2:
	s_cmp_lg_u64 s[52:53], 0
	s_cbranch_scc0 .Lap0_slowl2
	s_ff1_i32_b64 s56, s[52:53]
	s_bitset0_b64 s[52:53], s56
	v_readlane_b32 s29, v44, s56
	s_add_u32 s57, s57, 1
	s_lshl_b32 s1, s56, 2
	s_add_u32 s39, s63, s1

.Lap0_aftl2:
	s_waitcnt vmcnt(21)
	v_lshlrev_b32_e32 v192, 23, v78
	v_cvt_scalef32_pk32_f32_fp6 v[112:143], v[72:77], v192
	s_bitcmp1_b32 s51, 31
	s_cbranch_scc1 .Lap0_cB3
	v_fma_mix_f32 v144, v112, v4, 0 op_sel_hi:[0,1,0]
	v_fma_mix_f32 v145, v113, v4, 0 op_sel:[0,1,0] op_sel_hi:[0,1,0]
	v_fma_mix_f32 v144, v114, v5, v144 op_sel_hi:[0,1,0]
	v_fma_mix_f32 v145, v115, v5, v145 op_sel:[0,1,0] op_sel_hi:[0,1,0]
	v_fma_mix_f32 v144, v116, v6, v144 op_sel_hi:[0,1,0]
	v_fma_mix_f32 v145, v117, v6, v145 op_sel:[0,1,0] op_sel_hi:[0,1,0]
	v_fma_mix_f32 v144, v118, v7, v144 op_sel_hi:[0,1,0]
	v_fma_mix_f32 v145, v119, v7, v145 op_sel:[0,1,0] op_sel_hi:[0,1,0]
	v_fma_mix_f32 v144, v120, v8, v144 op_sel_hi:[0,1,0]
	v_fma_mix_f32 v145, v121, v8, v145 op_sel:[0,1,0] op_sel_hi:[0,1,0]
	v_fma_mix_f32 v144, v122, v9, v144 op_sel_hi:[0,1,0]
	v_fma_mix_f32 v145, v123, v9, v145 op_sel:[0,1,0] op_sel_hi:[0,1,0]
	v_fma_mix_f32 v144, v124, v10, v144 op_sel_hi:[0,1,0]
	v_fma_mix_f32 v145, v125, v10, v145 op_sel:[0,1,0] op_sel_hi:[0,1,0]
	v_fma_mix_f32 v144, v126, v11, v144 op_sel_hi:[0,1,0]
	v_fma_mix_f32 v145, v127, v11, v145 op_sel:[0,1,0] op_sel_hi:[0,1,0]
	v_fma_mix_f32 v144, v128, v12, v144 op_sel_hi:[0,1,0]
	v_fma_mix_f32 v145, v129, v12, v145 op_sel:[0,1,0] op_sel_hi:[0,1,0]
	v_fma_mix_f32 v144, v130, v13, v144 op_sel_hi:[0,1,0]
	v_fma_mix_f32 v145, v131, v13, v145 op_sel:[0,1,0] op_sel_hi:[0,1,0]
	v_fma_mix_f32 v144, v132, v14, v144 op_sel_hi:[0,1,0]
	v_fma_mix_f32 v145, v133, v14, v145 op_sel:[0,1,0] op_sel_hi:[0,1,0]
	v_fma_mix_f32 v144, v134, v15, v144 op_sel_hi:[0,1,0]
	v_fma_mix_f32 v145, v135, v15, v145 op_sel:[0,1,0] op_sel_hi:[0,1,0]
	v_fma_mix_f32 v144, v136, v16, v144 op_sel_hi:[0,1,0]
	v_fma_mix_f32 v145, v137, v16, v145 op_sel:[0,1,0] op_sel_hi:[0,1,0]
	v_fma_mix_f32 v144, v138, v17, v144 op_sel_hi:[0,1,0]
	v_fma_mix_f32 v145, v139, v17, v145 op_sel:[0,1,0] op_sel_hi:[0,1,0]
	v_fma_mix_f32 v144, v140, v18, v144 op_sel_hi:[0,1,0]
	v_fma_mix_f32 v145, v141, v18, v145 op_sel:[0,1,0] op_sel_hi:[0,1,0]
	v_fma_mix_f32 v144, v142, v19, v144 op_sel_hi:[0,1,0]
	v_fma_mix_f32 v145, v143, v19, v145 op_sel:[0,1,0] op_sel_hi:[0,1,0]
	v_add_f32_e32 v149, v144, v145
	s_branch .Lap0_cD3
.Lap0_cB3:
	v_fma_mix_f32 v144, v112, v20, 0 op_sel_hi:[0,1,0]
	v_fma_mix_f32 v145, v113, v20, 0 op_sel:[0,1,0] op_sel_hi:[0,1,0]
	v_fma_mix_f32 v144, v114, v21, v144 op_sel_hi:[0,1,0]
	v_fma_mix_f32 v145, v115, v21, v145 op_sel:[0,1,0] op_sel_hi:[0,1,0]
	v_fma_mix_f32 v144, v116, v22, v144 op_sel_hi:[0,1,0]
	v_fma_mix_f32 v145, v117, v22, v145 op_sel:[0,1,0] op_sel_hi:[0,1,0]
	v_fma_mix_f32 v144, v118, v23, v144 op_sel_hi:[0,1,0]
	v_fma_mix_f32 v145, v119, v23, v145 op_sel:[0,1,0] op_sel_hi:[0,1,0]
	v_fma_mix_f32 v144, v120, v24, v144 op_sel_hi:[0,1,0]
	v_fma_mix_f32 v145, v121, v24, v145 op_sel:[0,1,0] op_sel_hi:[0,1,0]
	v_fma_mix_f32 v144, v122, v25, v144 op_sel_hi:[0,1,0]
	v_fma_mix_f32 v145, v123, v25, v145 op_sel:[0,1,0] op_sel_hi:[0,1,0]
	v_fma_mix_f32 v144, v124, v26, v144 op_sel_hi:[0,1,0]
	v_fma_mix_f32 v145, v125, v26, v145 op_sel:[0,1,0] op_sel_hi:[0,1,0]
	v_fma_mix_f32 v144, v126, v27, v144 op_sel_hi:[0,1,0]
	v_fma_mix_f32 v145, v127, v27, v145 op_sel:[0,1,0] op_sel_hi:[0,1,0]
	v_fma_mix_f32 v144, v128, v28, v144 op_sel_hi:[0,1,0]
	v_fma_mix_f32 v145, v129, v28, v145 op_sel:[0,1,0] op_sel_hi:[0,1,0]
	v_fma_mix_f32 v144, v130, v29, v144 op_sel_hi:[0,1,0]
	v_fma_mix_f32 v145, v131, v29, v145 op_sel:[0,1,0] op_sel_hi:[0,1,0]
	v_fma_mix_f32 v144, v132, v30, v144 op_sel_hi:[0,1,0]
	v_fma_mix_f32 v145, v133, v30, v145 op_sel:[0,1,0] op_sel_hi:[0,1,0]
	v_fma_mix_f32 v144, v134, v31, v144 op_sel_hi:[0,1,0]
	v_fma_mix_f32 v145, v135, v31, v145 op_sel:[0,1,0] op_sel_hi:[0,1,0]
	v_fma_mix_f32 v144, v136, v32, v144 op_sel_hi:[0,1,0]
	v_fma_mix_f32 v145, v137, v32, v145 op_sel:[0,1,0] op_sel_hi:[0,1,0]
	v_fma_mix_f32 v144, v138, v33, v144 op_sel_hi:[0,1,0]
	v_fma_mix_f32 v145, v139, v33, v145 op_sel:[0,1,0] op_sel_hi:[0,1,0]
	v_fma_mix_f32 v144, v140, v34, v144 op_sel_hi:[0,1,0]
	v_fma_mix_f32 v145, v141, v34, v145 op_sel:[0,1,0] op_sel_hi:[0,1,0]
	v_fma_mix_f32 v144, v142, v35, v144 op_sel_hi:[0,1,0]
	v_fma_mix_f32 v145, v143, v35, v145 op_sel:[0,1,0] op_sel_hi:[0,1,0]
	v_add_f32_e32 v149, v144, v145
.Lap0_cD3:
	s_bitset0_b32 s51, 31
	v_writelane_b32 v45, s51, 5
.Lap0_issl3:
	s_cmp_lg_u64 s[52:53], 0
	s_cbranch_scc0 .Lap0_slowl3
	s_ff1_i32_b64 s56, s[52:53]
	s_bitset0_b64 s[52:53], s56
	v_readlane_b32 s29, v44, s56
	s_add_u32 s57, s57, 1
	s_lshl_b32 s1, s56, 2
	s_add_u32 s51, s63, s1

.Lap0_aftl3:
	s_waitcnt vmcnt(21)
	v_lshlrev_b32_e32 v192, 23, v86
	v_cvt_scalef32_pk32_f32_fp6 v[112:143], v[80:85], v192
	s_bitcmp1_b32 s28, 31
	s_cbranch_scc1 .Lap0_cB4
	v_fma_mix_f32 v144, v112, v4, 0 op_sel_hi:[0,1,0]
	v_fma_mix_f32 v145, v113, v4, 0 op_sel:[0,1,0] op_sel_hi:[0,1,0]
	v_fma_mix_f32 v144, v114, v5, v144 op_sel_hi:[0,1,0]
	v_fma_mix_f32 v145, v115, v5, v145 op_sel:[0,1,0] op_sel_hi:[0,1,0]
	v_fma_mix_f32 v144, v116, v6, v144 op_sel_hi:[0,1,0]
	v_fma_mix_f32 v145, v117, v6, v145 op_sel:[0,1,0] op_sel_hi:[0,1,0]
	v_fma_mix_f32 v144, v118, v7, v144 op_sel_hi:[0,1,0]
	v_fma_mix_f32 v145, v119, v7, v145 op_sel:[0,1,0] op_sel_hi:[0,1,0]
	v_fma_mix_f32 v144, v120, v8, v144 op_sel_hi:[0,1,0]
	v_fma_mix_f32 v145, v121, v8, v145 op_sel:[0,1,0] op_sel_hi:[0,1,0]
	v_fma_mix_f32 v144, v122, v9, v144 op_sel_hi:[0,1,0]
	v_fma_mix_f32 v145, v123, v9, v145 op_sel:[0,1,0] op_sel_hi:[0,1,0]
	v_fma_mix_f32 v144, v124, v10, v144 op_sel_hi:[0,1,0]
	v_fma_mix_f32 v145, v125, v10, v145 op_sel:[0,1,0] op_sel_hi:[0,1,0]
	v_fma_mix_f32 v144, v126, v11, v144 op_sel_hi:[0,1,0]
	v_fma_mix_f32 v145, v127, v11, v145 op_sel:[0,1,0] op_sel_hi:[0,1,0]
	v_fma_mix_f32 v144, v128, v12, v144 op_sel_hi:[0,1,0]
	v_fma_mix_f32 v145, v129, v12, v145 op_sel:[0,1,0] op_sel_hi:[0,1,0]
	v_fma_mix_f32 v144, v130, v13, v144 op_sel_hi:[0,1,0]
	v_fma_mix_f32 v145, v131, v13, v145 op_sel:[0,1,0] op_sel_hi:[0,1,0]
	v_fma_mix_f32 v144, v132, v14, v144 op_sel_hi:[0,1,0]
	v_fma_mix_f32 v145, v133, v14, v145 op_sel:[0,1,0] op_sel_hi:[0,1,0]
	v_fma_mix_f32 v144, v134, v15, v144 op_sel_hi:[0,1,0]
	v_fma_mix_f32 v145, v135, v15, v145 op_sel:[0,1,0] op_sel_hi:[0,1,0]
	v_fma_mix_f32 v144, v136, v16, v144 op_sel_hi:[0,1,0]
	v_fma_mix_f32 v145, v137, v16, v145 op_sel:[0,1,0] op_sel_hi:[0,1,0]
	v_fma_mix_f32 v144, v138, v17, v144 op_sel_hi:[0,1,0]
	v_fma_mix_f32 v145, v139, v17, v145 op_sel:[0,1,0] op_sel_hi:[0,1,0]
	v_fma_mix_f32 v144, v140, v18, v144 op_sel_hi:[0,1,0]
	v_fma_mix_f32 v145, v141, v18, v145 op_sel:[0,1,0] op_sel_hi:[0,1,0]
	v_fma_mix_f32 v144, v142, v19, v144 op_sel_hi:[0,1,0]
	v_fma_mix_f32 v145, v143, v19, v145 op_sel:[0,1,0] op_sel_hi:[0,1,0]
	v_add_f32_e32 v150, v144, v145
	s_branch .Lap0_cD4
.Lap0_cB4:
	v_fma_mix_f32 v144, v112, v20, 0 op_sel_hi:[0,1,0]
	v_fma_mix_f32 v145, v113, v20, 0 op_sel:[0,1,0] op_sel_hi:[0,1,0]
	v_fma_mix_f32 v144, v114, v21, v144 op_sel_hi:[0,1,0]
	v_fma_mix_f32 v145, v115, v21, v145 op_sel:[0,1,0] op_sel_hi:[0,1,0]
	v_fma_mix_f32 v144, v116, v22, v144 op_sel_hi:[0,1,0]
	v_fma_mix_f32 v145, v117, v22, v145 op_sel:[0,1,0] op_sel_hi:[0,1,0]
	v_fma_mix_f32 v144, v118, v23, v144 op_sel_hi:[0,1,0]
	v_fma_mix_f32 v145, v119, v23, v145 op_sel:[0,1,0] op_sel_hi:[0,1,0]
	v_fma_mix_f32 v144, v120, v24, v144 op_sel_hi:[0,1,0]
	v_fma_mix_f32 v145, v121, v24, v145 op_sel:[0,1,0] op_sel_hi:[0,1,0]
	v_fma_mix_f32 v144, v122, v25, v144 op_sel_hi:[0,1,0]
	v_fma_mix_f32 v145, v123, v25, v145 op_sel:[0,1,0] op_sel_hi:[0,1,0]
	v_fma_mix_f32 v144, v124, v26, v144 op_sel_hi:[0,1,0]
	v_fma_mix_f32 v145, v125, v26, v145 op_sel:[0,1,0] op_sel_hi:[0,1,0]
	v_fma_mix_f32 v144, v126, v27, v144 op_sel_hi:[0,1,0]
	v_fma_mix_f32 v145, v127, v27, v145 op_sel:[0,1,0] op_sel_hi:[0,1,0]
	v_fma_mix_f32 v144, v128, v28, v144 op_sel_hi:[0,1,0]
	v_fma_mix_f32 v145, v129, v28, v145 op_sel:[0,1,0] op_sel_hi:[0,1,0]
	v_fma_mix_f32 v144, v130, v29, v144 op_sel_hi:[0,1,0]
	v_fma_mix_f32 v145, v131, v29, v145 op_sel:[0,1,0] op_sel_hi:[0,1,0]
	v_fma_mix_f32 v144, v132, v30, v144 op_sel_hi:[0,1,0]
	v_fma_mix_f32 v145, v133, v30, v145 op_sel:[0,1,0] op_sel_hi:[0,1,0]
	v_fma_mix_f32 v144, v134, v31, v144 op_sel_hi:[0,1,0]
	v_fma_mix_f32 v145, v135, v31, v145 op_sel:[0,1,0] op_sel_hi:[0,1,0]
	v_fma_mix_f32 v144, v136, v32, v144 op_sel_hi:[0,1,0]
	v_fma_mix_f32 v145, v137, v32, v145 op_sel:[0,1,0] op_sel_hi:[0,1,0]
	v_fma_mix_f32 v144, v138, v33, v144 op_sel_hi:[0,1,0]
	v_fma_mix_f32 v145, v139, v33, v145 op_sel:[0,1,0] op_sel_hi:[0,1,0]
	v_fma_mix_f32 v144, v140, v34, v144 op_sel_hi:[0,1,0]
	v_fma_mix_f32 v145, v141, v34, v145 op_sel:[0,1,0] op_sel_hi:[0,1,0]
	v_fma_mix_f32 v144, v142, v35, v144 op_sel_hi:[0,1,0]
	v_fma_mix_f32 v145, v143, v35, v145 op_sel:[0,1,0] op_sel_hi:[0,1,0]
	v_add_f32_e32 v150, v144, v145
.Lap0_cD4:
	s_bitset0_b32 s28, 31
	v_writelane_b32 v45, s28, 8
.Lap0_issl4:
	s_cmp_lg_u64 s[52:53], 0
	s_cbranch_scc0 .Lap0_slowl4
	s_ff1_i32_b64 s56, s[52:53]
	s_bitset0_b64 s[52:53], s56
	v_readlane_b32 s29, v44, s56
	s_add_u32 s57, s57, 1
	s_lshl_b32 s1, s56, 2
	s_add_u32 s28, s63, s1

.Lap0_aftl4:
	s_waitcnt vmcnt(21)
	v_lshlrev_b32_e32 v192, 23, v94
	v_cvt_scalef32_pk32_f32_fp6 v[112:143], v[88:93], v192
	s_bitcmp1_b32 s30, 31
	s_cbranch_scc1 .Lap0_cB5
	v_fma_mix_f32 v144, v112, v4, 0 op_sel_hi:[0,1,0]
	v_fma_mix_f32 v145, v113, v4, 0 op_sel:[0,1,0] op_sel_hi:[0,1,0]
	v_fma_mix_f32 v144, v114, v5, v144 op_sel_hi:[0,1,0]
	v_fma_mix_f32 v145, v115, v5, v145 op_sel:[0,1,0] op_sel_hi:[0,1,0]
	v_fma_mix_f32 v144, v116, v6, v144 op_sel_hi:[0,1,0]
	v_fma_mix_f32 v145, v117, v6, v145 op_sel:[0,1,0] op_sel_hi:[0,1,0]
	v_fma_mix_f32 v144, v118, v7, v144 op_sel_hi:[0,1,0]
	v_fma_mix_f32 v145, v119, v7, v145 op_sel:[0,1,0] op_sel_hi:[0,1,0]
	v_fma_mix_f32 v144, v120, v8, v144 op_sel_hi:[0,1,0]
	v_fma_mix_f32 v145, v121, v8, v145 op_sel:[0,1,0] op_sel_hi:[0,1,0]
	v_fma_mix_f32 v144, v122, v9, v144 op_sel_hi:[0,1,0]
	v_fma_mix_f32 v145, v123, v9, v145 op_sel:[0,1,0] op_sel_hi:[0,1,0]
	v_fma_mix_f32 v144, v124, v10, v144 op_sel_hi:[0,1,0]
	v_fma_mix_f32 v145, v125, v10, v145 op_sel:[0,1,0] op_sel_hi:[0,1,0]
	v_fma_mix_f32 v144, v126, v11, v144 op_sel_hi:[0,1,0]
	v_fma_mix_f32 v145, v127, v11, v145 op_sel:[0,1,0] op_sel_hi:[0,1,0]
	v_fma_mix_f32 v144, v128, v12, v144 op_sel_hi:[0,1,0]
	v_fma_mix_f32 v145, v129, v12, v145 op_sel:[0,1,0] op_sel_hi:[0,1,0]
	v_fma_mix_f32 v144, v130, v13, v144 op_sel_hi:[0,1,0]
	v_fma_mix_f32 v145, v131, v13, v145 op_sel:[0,1,0] op_sel_hi:[0,1,0]
	v_fma_mix_f32 v144, v132, v14, v144 op_sel_hi:[0,1,0]
	v_fma_mix_f32 v145, v133, v14, v145 op_sel:[0,1,0] op_sel_hi:[0,1,0]
	v_fma_mix_f32 v144, v134, v15, v144 op_sel_hi:[0,1,0]
	v_fma_mix_f32 v145, v135, v15, v145 op_sel:[0,1,0] op_sel_hi:[0,1,0]
	v_fma_mix_f32 v144, v136, v16, v144 op_sel_hi:[0,1,0]
	v_fma_mix_f32 v145, v137, v16, v145 op_sel:[0,1,0] op_sel_hi:[0,1,0]
	v_fma_mix_f32 v144, v138, v17, v144 op_sel_hi:[0,1,0]
	v_fma_mix_f32 v145, v139, v17, v145 op_sel:[0,1,0] op_sel_hi:[0,1,0]
	v_fma_mix_f32 v144, v140, v18, v144 op_sel_hi:[0,1,0]
	v_fma_mix_f32 v145, v141, v18, v145 op_sel:[0,1,0] op_sel_hi:[0,1,0]
	v_fma_mix_f32 v144, v142, v19, v144 op_sel_hi:[0,1,0]
	v_fma_mix_f32 v145, v143, v19, v145 op_sel:[0,1,0] op_sel_hi:[0,1,0]
	v_add_f32_e32 v151, v144, v145
	s_branch .Lap0_cD5
.Lap0_cB5:
	v_fma_mix_f32 v144, v112, v20, 0 op_sel_hi:[0,1,0]
	v_fma_mix_f32 v145, v113, v20, 0 op_sel:[0,1,0] op_sel_hi:[0,1,0]
	v_fma_mix_f32 v144, v114, v21, v144 op_sel_hi:[0,1,0]
	v_fma_mix_f32 v145, v115, v21, v145 op_sel:[0,1,0] op_sel_hi:[0,1,0]
	v_fma_mix_f32 v144, v116, v22, v144 op_sel_hi:[0,1,0]
	v_fma_mix_f32 v145, v117, v22, v145 op_sel:[0,1,0] op_sel_hi:[0,1,0]
	v_fma_mix_f32 v144, v118, v23, v144 op_sel_hi:[0,1,0]
	v_fma_mix_f32 v145, v119, v23, v145 op_sel:[0,1,0] op_sel_hi:[0,1,0]
	v_fma_mix_f32 v144, v120, v24, v144 op_sel_hi:[0,1,0]
	v_fma_mix_f32 v145, v121, v24, v145 op_sel:[0,1,0] op_sel_hi:[0,1,0]
	v_fma_mix_f32 v144, v122, v25, v144 op_sel_hi:[0,1,0]
	v_fma_mix_f32 v145, v123, v25, v145 op_sel:[0,1,0] op_sel_hi:[0,1,0]
	v_fma_mix_f32 v144, v124, v26, v144 op_sel_hi:[0,1,0]
	v_fma_mix_f32 v145, v125, v26, v145 op_sel:[0,1,0] op_sel_hi:[0,1,0]
	v_fma_mix_f32 v144, v126, v27, v144 op_sel_hi:[0,1,0]
	v_fma_mix_f32 v145, v127, v27, v145 op_sel:[0,1,0] op_sel_hi:[0,1,0]
	v_fma_mix_f32 v144, v128, v28, v144 op_sel_hi:[0,1,0]
	v_fma_mix_f32 v145, v129, v28, v145 op_sel:[0,1,0] op_sel_hi:[0,1,0]
	v_fma_mix_f32 v144, v130, v29, v144 op_sel_hi:[0,1,0]
	v_fma_mix_f32 v145, v131, v29, v145 op_sel:[0,1,0] op_sel_hi:[0,1,0]
	v_fma_mix_f32 v144, v132, v30, v144 op_sel_hi:[0,1,0]
	v_fma_mix_f32 v145, v133, v30, v145 op_sel:[0,1,0] op_sel_hi:[0,1,0]
	v_fma_mix_f32 v144, v134, v31, v144 op_sel_hi:[0,1,0]
	v_fma_mix_f32 v145, v135, v31, v145 op_sel:[0,1,0] op_sel_hi:[0,1,0]
	v_fma_mix_f32 v144, v136, v32, v144 op_sel_hi:[0,1,0]
	v_fma_mix_f32 v145, v137, v32, v145 op_sel:[0,1,0] op_sel_hi:[0,1,0]
	v_fma_mix_f32 v144, v138, v33, v144 op_sel_hi:[0,1,0]
	v_fma_mix_f32 v145, v139, v33, v145 op_sel:[0,1,0] op_sel_hi:[0,1,0]
	v_fma_mix_f32 v144, v140, v34, v144 op_sel_hi:[0,1,0]
	v_fma_mix_f32 v145, v141, v34, v145 op_sel:[0,1,0] op_sel_hi:[0,1,0]
	v_fma_mix_f32 v144, v142, v35, v144 op_sel_hi:[0,1,0]
	v_fma_mix_f32 v145, v143, v35, v145 op_sel:[0,1,0] op_sel_hi:[0,1,0]
	v_add_f32_e32 v151, v144, v145
.Lap0_cD5:
	s_bitset0_b32 s30, 31
	v_writelane_b32 v45, s30, 9
.Lap0_issl5:
	s_cmp_lg_u64 s[52:53], 0
	s_cbranch_scc0 .Lap0_slowl5
	s_ff1_i32_b64 s56, s[52:53]
	s_bitset0_b64 s[52:53], s56
	v_readlane_b32 s29, v44, s56
	s_add_u32 s57, s57, 1
	s_lshl_b32 s1, s56, 2
	s_add_u32 s30, s63, s1

.Lap0_aftl5:
	s_waitcnt vmcnt(21)
	v_lshlrev_b32_e32 v192, 23, v102
	v_cvt_scalef32_pk32_f32_fp6 v[112:143], v[96:101], v192
	s_bitcmp1_b32 s36, 31
	s_cbranch_scc1 .Lap0_cB6
	v_fma_mix_f32 v144, v112, v4, 0 op_sel_hi:[0,1,0]
	v_fma_mix_f32 v145, v113, v4, 0 op_sel:[0,1,0] op_sel_hi:[0,1,0]
	v_fma_mix_f32 v144, v114, v5, v144 op_sel_hi:[0,1,0]
	v_fma_mix_f32 v145, v115, v5, v145 op_sel:[0,1,0] op_sel_hi:[0,1,0]
	v_fma_mix_f32 v144, v116, v6, v144 op_sel_hi:[0,1,0]
	v_fma_mix_f32 v145, v117, v6, v145 op_sel:[0,1,0] op_sel_hi:[0,1,0]
	v_fma_mix_f32 v144, v118, v7, v144 op_sel_hi:[0,1,0]
	v_fma_mix_f32 v145, v119, v7, v145 op_sel:[0,1,0] op_sel_hi:[0,1,0]
	v_fma_mix_f32 v144, v120, v8, v144 op_sel_hi:[0,1,0]
	v_fma_mix_f32 v145, v121, v8, v145 op_sel:[0,1,0] op_sel_hi:[0,1,0]
	v_fma_mix_f32 v144, v122, v9, v144 op_sel_hi:[0,1,0]
	v_fma_mix_f32 v145, v123, v9, v145 op_sel:[0,1,0] op_sel_hi:[0,1,0]
	v_fma_mix_f32 v144, v124, v10, v144 op_sel_hi:[0,1,0]
	v_fma_mix_f32 v145, v125, v10, v145 op_sel:[0,1,0] op_sel_hi:[0,1,0]
	v_fma_mix_f32 v144, v126, v11, v144 op_sel_hi:[0,1,0]
	v_fma_mix_f32 v145, v127, v11, v145 op_sel:[0,1,0] op_sel_hi:[0,1,0]
	v_fma_mix_f32 v144, v128, v12, v144 op_sel_hi:[0,1,0]
	v_fma_mix_f32 v145, v129, v12, v145 op_sel:[0,1,0] op_sel_hi:[0,1,0]
	v_fma_mix_f32 v144, v130, v13, v144 op_sel_hi:[0,1,0]
	v_fma_mix_f32 v145, v131, v13, v145 op_sel:[0,1,0] op_sel_hi:[0,1,0]
	v_fma_mix_f32 v144, v132, v14, v144 op_sel_hi:[0,1,0]
	v_fma_mix_f32 v145, v133, v14, v145 op_sel:[0,1,0] op_sel_hi:[0,1,0]
	v_fma_mix_f32 v144, v134, v15, v144 op_sel_hi:[0,1,0]
	v_fma_mix_f32 v145, v135, v15, v145 op_sel:[0,1,0] op_sel_hi:[0,1,0]
	v_fma_mix_f32 v144, v136, v16, v144 op_sel_hi:[0,1,0]
	v_fma_mix_f32 v145, v137, v16, v145 op_sel:[0,1,0] op_sel_hi:[0,1,0]
	v_fma_mix_f32 v144, v138, v17, v144 op_sel_hi:[0,1,0]
	v_fma_mix_f32 v145, v139, v17, v145 op_sel:[0,1,0] op_sel_hi:[0,1,0]
	v_fma_mix_f32 v144, v140, v18, v144 op_sel_hi:[0,1,0]
	v_fma_mix_f32 v145, v141, v18, v145 op_sel:[0,1,0] op_sel_hi:[0,1,0]
	v_fma_mix_f32 v144, v142, v19, v144 op_sel_hi:[0,1,0]
	v_fma_mix_f32 v145, v143, v19, v145 op_sel:[0,1,0] op_sel_hi:[0,1,0]
	v_add_f32_e32 v152, v144, v145
	s_branch .Lap0_cD6
.Lap0_cB6:
	v_fma_mix_f32 v144, v112, v20, 0 op_sel_hi:[0,1,0]
	v_fma_mix_f32 v145, v113, v20, 0 op_sel:[0,1,0] op_sel_hi:[0,1,0]
	v_fma_mix_f32 v144, v114, v21, v144 op_sel_hi:[0,1,0]
	v_fma_mix_f32 v145, v115, v21, v145 op_sel:[0,1,0] op_sel_hi:[0,1,0]
	v_fma_mix_f32 v144, v116, v22, v144 op_sel_hi:[0,1,0]
	v_fma_mix_f32 v145, v117, v22, v145 op_sel:[0,1,0] op_sel_hi:[0,1,0]
	v_fma_mix_f32 v144, v118, v23, v144 op_sel_hi:[0,1,0]
	v_fma_mix_f32 v145, v119, v23, v145 op_sel:[0,1,0] op_sel_hi:[0,1,0]
	v_fma_mix_f32 v144, v120, v24, v144 op_sel_hi:[0,1,0]
	v_fma_mix_f32 v145, v121, v24, v145 op_sel:[0,1,0] op_sel_hi:[0,1,0]
	v_fma_mix_f32 v144, v122, v25, v144 op_sel_hi:[0,1,0]
	v_fma_mix_f32 v145, v123, v25, v145 op_sel:[0,1,0] op_sel_hi:[0,1,0]
	v_fma_mix_f32 v144, v124, v26, v144 op_sel_hi:[0,1,0]
	v_fma_mix_f32 v145, v125, v26, v145 op_sel:[0,1,0] op_sel_hi:[0,1,0]
	v_fma_mix_f32 v144, v126, v27, v144 op_sel_hi:[0,1,0]
	v_fma_mix_f32 v145, v127, v27, v145 op_sel:[0,1,0] op_sel_hi:[0,1,0]
	v_fma_mix_f32 v144, v128, v28, v144 op_sel_hi:[0,1,0]
	v_fma_mix_f32 v145, v129, v28, v145 op_sel:[0,1,0] op_sel_hi:[0,1,0]
	v_fma_mix_f32 v144, v130, v29, v144 op_sel_hi:[0,1,0]
	v_fma_mix_f32 v145, v131, v29, v145 op_sel:[0,1,0] op_sel_hi:[0,1,0]
	v_fma_mix_f32 v144, v132, v30, v144 op_sel_hi:[0,1,0]
	v_fma_mix_f32 v145, v133, v30, v145 op_sel:[0,1,0] op_sel_hi:[0,1,0]
	v_fma_mix_f32 v144, v134, v31, v144 op_sel_hi:[0,1,0]
	v_fma_mix_f32 v145, v135, v31, v145 op_sel:[0,1,0] op_sel_hi:[0,1,0]
	v_fma_mix_f32 v144, v136, v32, v144 op_sel_hi:[0,1,0]
	v_fma_mix_f32 v145, v137, v32, v145 op_sel:[0,1,0] op_sel_hi:[0,1,0]
	v_fma_mix_f32 v144, v138, v33, v144 op_sel_hi:[0,1,0]
	v_fma_mix_f32 v145, v139, v33, v145 op_sel:[0,1,0] op_sel_hi:[0,1,0]
	v_fma_mix_f32 v144, v140, v34, v144 op_sel_hi:[0,1,0]
	v_fma_mix_f32 v145, v141, v34, v145 op_sel:[0,1,0] op_sel_hi:[0,1,0]
	v_fma_mix_f32 v144, v142, v35, v144 op_sel_hi:[0,1,0]
	v_fma_mix_f32 v145, v143, v35, v145 op_sel:[0,1,0] op_sel_hi:[0,1,0]
	v_add_f32_e32 v152, v144, v145
.Lap0_cD6:
	s_bitset0_b32 s36, 31
	v_writelane_b32 v45, s36, 12
.Lap0_issl6:
	s_cmp_lg_u64 s[52:53], 0
	s_cbranch_scc0 .Lap0_slowl6
	s_ff1_i32_b64 s56, s[52:53]
	s_bitset0_b64 s[52:53], s56
	v_readlane_b32 s29, v44, s56
	s_add_u32 s57, s57, 1
	s_lshl_b32 s1, s56, 2
	s_add_u32 s36, s63, s1

.Lap0_aftl6:
	s_waitcnt vmcnt(21)
	v_lshlrev_b32_e32 v192, 23, v110
	v_cvt_scalef32_pk32_f32_fp6 v[112:143], v[104:109], v192
	s_bitcmp1_b32 s37, 31
	s_cbranch_scc1 .Lap0_cB7
	v_fma_mix_f32 v144, v112, v4, 0 op_sel_hi:[0,1,0]
	v_fma_mix_f32 v145, v113, v4, 0 op_sel:[0,1,0] op_sel_hi:[0,1,0]
	v_fma_mix_f32 v144, v114, v5, v144 op_sel_hi:[0,1,0]
	v_fma_mix_f32 v145, v115, v5, v145 op_sel:[0,1,0] op_sel_hi:[0,1,0]
	v_fma_mix_f32 v144, v116, v6, v144 op_sel_hi:[0,1,0]
	v_fma_mix_f32 v145, v117, v6, v145 op_sel:[0,1,0] op_sel_hi:[0,1,0]
	v_fma_mix_f32 v144, v118, v7, v144 op_sel_hi:[0,1,0]
	v_fma_mix_f32 v145, v119, v7, v145 op_sel:[0,1,0] op_sel_hi:[0,1,0]
	v_fma_mix_f32 v144, v120, v8, v144 op_sel_hi:[0,1,0]
	v_fma_mix_f32 v145, v121, v8, v145 op_sel:[0,1,0] op_sel_hi:[0,1,0]
	v_fma_mix_f32 v144, v122, v9, v144 op_sel_hi:[0,1,0]
	v_fma_mix_f32 v145, v123, v9, v145 op_sel:[0,1,0] op_sel_hi:[0,1,0]
	v_fma_mix_f32 v144, v124, v10, v144 op_sel_hi:[0,1,0]
	v_fma_mix_f32 v145, v125, v10, v145 op_sel:[0,1,0] op_sel_hi:[0,1,0]
	v_fma_mix_f32 v144, v126, v11, v144 op_sel_hi:[0,1,0]
	v_fma_mix_f32 v145, v127, v11, v145 op_sel:[0,1,0] op_sel_hi:[0,1,0]
	v_fma_mix_f32 v144, v128, v12, v144 op_sel_hi:[0,1,0]
	v_fma_mix_f32 v145, v129, v12, v145 op_sel:[0,1,0] op_sel_hi:[0,1,0]
	v_fma_mix_f32 v144, v130, v13, v144 op_sel_hi:[0,1,0]
	v_fma_mix_f32 v145, v131, v13, v145 op_sel:[0,1,0] op_sel_hi:[0,1,0]
	v_fma_mix_f32 v144, v132, v14, v144 op_sel_hi:[0,1,0]
	v_fma_mix_f32 v145, v133, v14, v145 op_sel:[0,1,0] op_sel_hi:[0,1,0]
	v_fma_mix_f32 v144, v134, v15, v144 op_sel_hi:[0,1,0]
	v_fma_mix_f32 v145, v135, v15, v145 op_sel:[0,1,0] op_sel_hi:[0,1,0]
	v_fma_mix_f32 v144, v136, v16, v144 op_sel_hi:[0,1,0]
	v_fma_mix_f32 v145, v137, v16, v145 op_sel:[0,1,0] op_sel_hi:[0,1,0]
	v_fma_mix_f32 v144, v138, v17, v144 op_sel_hi:[0,1,0]
	v_fma_mix_f32 v145, v139, v17, v145 op_sel:[0,1,0] op_sel_hi:[0,1,0]
	v_fma_mix_f32 v144, v140, v18, v144 op_sel_hi:[0,1,0]
	v_fma_mix_f32 v145, v141, v18, v145 op_sel:[0,1,0] op_sel_hi:[0,1,0]
	v_fma_mix_f32 v144, v142, v19, v144 op_sel_hi:[0,1,0]
	v_fma_mix_f32 v145, v143, v19, v145 op_sel:[0,1,0] op_sel_hi:[0,1,0]
	v_add_f32_e32 v153, v144, v145
	s_branch .Lap0_cD7
.Lap0_cB7:
	v_fma_mix_f32 v144, v112, v20, 0 op_sel_hi:[0,1,0]
	v_fma_mix_f32 v145, v113, v20, 0 op_sel:[0,1,0] op_sel_hi:[0,1,0]
	v_fma_mix_f32 v144, v114, v21, v144 op_sel_hi:[0,1,0]
	v_fma_mix_f32 v145, v115, v21, v145 op_sel:[0,1,0] op_sel_hi:[0,1,0]
	v_fma_mix_f32 v144, v116, v22, v144 op_sel_hi:[0,1,0]
	v_fma_mix_f32 v145, v117, v22, v145 op_sel:[0,1,0] op_sel_hi:[0,1,0]
	v_fma_mix_f32 v144, v118, v23, v144 op_sel_hi:[0,1,0]
	v_fma_mix_f32 v145, v119, v23, v145 op_sel:[0,1,0] op_sel_hi:[0,1,0]
	v_fma_mix_f32 v144, v120, v24, v144 op_sel_hi:[0,1,0]
	v_fma_mix_f32 v145, v121, v24, v145 op_sel:[0,1,0] op_sel_hi:[0,1,0]
	v_fma_mix_f32 v144, v122, v25, v144 op_sel_hi:[0,1,0]
	v_fma_mix_f32 v145, v123, v25, v145 op_sel:[0,1,0] op_sel_hi:[0,1,0]
	v_fma_mix_f32 v144, v124, v26, v144 op_sel_hi:[0,1,0]
	v_fma_mix_f32 v145, v125, v26, v145 op_sel:[0,1,0] op_sel_hi:[0,1,0]
	v_fma_mix_f32 v144, v126, v27, v144 op_sel_hi:[0,1,0]
	v_fma_mix_f32 v145, v127, v27, v145 op_sel:[0,1,0] op_sel_hi:[0,1,0]
	v_fma_mix_f32 v144, v128, v28, v144 op_sel_hi:[0,1,0]
	v_fma_mix_f32 v145, v129, v28, v145 op_sel:[0,1,0] op_sel_hi:[0,1,0]
	v_fma_mix_f32 v144, v130, v29, v144 op_sel_hi:[0,1,0]
	v_fma_mix_f32 v145, v131, v29, v145 op_sel:[0,1,0] op_sel_hi:[0,1,0]
	v_fma_mix_f32 v144, v132, v30, v144 op_sel_hi:[0,1,0]
	v_fma_mix_f32 v145, v133, v30, v145 op_sel:[0,1,0] op_sel_hi:[0,1,0]
	v_fma_mix_f32 v144, v134, v31, v144 op_sel_hi:[0,1,0]
	v_fma_mix_f32 v145, v135, v31, v145 op_sel:[0,1,0] op_sel_hi:[0,1,0]
	v_fma_mix_f32 v144, v136, v32, v144 op_sel_hi:[0,1,0]
	v_fma_mix_f32 v145, v137, v32, v145 op_sel:[0,1,0] op_sel_hi:[0,1,0]
	v_fma_mix_f32 v144, v138, v33, v144 op_sel_hi:[0,1,0]
	v_fma_mix_f32 v145, v139, v33, v145 op_sel:[0,1,0] op_sel_hi:[0,1,0]
	v_fma_mix_f32 v144, v140, v34, v144 op_sel_hi:[0,1,0]
	v_fma_mix_f32 v145, v141, v34, v145 op_sel:[0,1,0] op_sel_hi:[0,1,0]
	v_fma_mix_f32 v144, v142, v35, v144 op_sel_hi:[0,1,0]
	v_fma_mix_f32 v145, v143, v35, v145 op_sel:[0,1,0] op_sel_hi:[0,1,0]
	v_add_f32_e32 v153, v144, v145
.Lap0_cD7:
	s_bitset0_b32 s37, 31
	v_writelane_b32 v45, s37, 13
.Lap0_issl7:
	s_cmp_lg_u64 s[52:53], 0
	s_cbranch_scc0 .Lap0_slowl7
	s_ff1_i32_b64 s56, s[52:53]
	s_bitset0_b64 s[52:53], s56
	v_readlane_b32 s29, v44, s56
	s_add_u32 s57, s57, 1
	s_lshl_b32 s1, s56, 2
	s_add_u32 s37, s63, s1

; #define PB_FENCE asm volatile("" ::: "memory")
; __device__ __forceinline__ void ph_peer_apply(const Params& P, int layer, float* xlat, float* xctx_in, float* xctx_out, int nrows, bool write_next, char* smem, float* xlat_out = nullptr) {
;     ...
;     for (int gq = 0; gq < NG; gq += 2) {
;       PB_LOAD(bufB, tu, gq + 1); PB_FENCE;
;       PB_DOT(bufA, gq);
;       if (gq + 2 < NG) PB_LOAD(bufA, tu, gq + 2);
;       PB_FENCE;
;       PB_DOT(bufB, gq + 1);
;     }
.Lap0_aftl7:
	v_mov_b32_e32 v229, v45
	v_add_f32_dpp v146, v146, v146 row_ror:8 row_mask:0xf bank_mask:0xf bound_ctrl:1
	v_add_f32_dpp v147, v147, v147 row_ror:8 row_mask:0xf bank_mask:0xf bound_ctrl:1
	v_add_f32_dpp v148, v148, v148 row_ror:8 row_mask:0xf bank_mask:0xf bound_ctrl:1
	v_add_f32_dpp v149, v149, v149 row_ror:8 row_mask:0xf bank_mask:0xf bound_ctrl:1
	v_add_f32_dpp v146, v150, v150 row_ror:8 row_mask:0xf bank_mask:0xc bound_ctrl:1
	v_add_f32_dpp v147, v151, v151 row_ror:8 row_mask:0xf bank_mask:0xc bound_ctrl:1
	v_add_f32_dpp v148, v152, v152 row_ror:8 row_mask:0xf bank_mask:0xc bound_ctrl:1
	v_add_f32_dpp v149, v153, v153 row_ror:8 row_mask:0xf bank_mask:0xc bound_ctrl:1
	v_add_f32_dpp v146, v146, v146 row_half_mirror row_mask:0xf bank_mask:0xf bound_ctrl:1
	v_add_f32_dpp v147, v147, v147 row_half_mirror row_mask:0xf bank_mask:0xf bound_ctrl:1
	v_add_f32_dpp v146, v148, v148 row_half_mirror row_mask:0xf bank_mask:0xa bound_ctrl:1
	v_add_f32_dpp v147, v149, v149 row_half_mirror row_mask:0xf bank_mask:0xa bound_ctrl:1
	s_nop 1
	v_add_f32_dpp v146, v146, v146 quad_perm:[1,0,3,2] row_mask:0xf bank_mask:0xf bound_ctrl:1
	v_add_f32_dpp v147, v147, v147 quad_perm:[1,0,3,2] row_mask:0xf bank_mask:0xf bound_ctrl:1
	s_nop 0
	v_add_f32_dpp v146, v146, v146 quad_perm:[2,3,0,1] row_mask:0xf bank_mask:0xf bound_ctrl:1
	v_add_f32_dpp v147, v147, v147 quad_perm:[2,3,0,1] row_mask:0xf bank_mask:0xf bound_ctrl:1
	v_mov_b32_e32 v193, v146
	v_mov_b32_e32 v194, v147
	s_nop 1
	v_permlane32_swap_b32_e32 v193, v146
	v_permlane32_swap_b32_e32 v194, v147
	v_add_f32_e32 v146, v146, v193
	v_add_f32_e32 v147, v147, v194
	v_mov_b32_e32 v193, v146
	v_mov_b32_e32 v194, v147
	s_nop 1
	v_permlane16_swap_b32_e32 v193, v146
	v_permlane16_swap_b32_e32 v194, v147
	v_add_f32_e32 v146, v146, v193
	v_add_f32_e32 v147, v147, v194
	v_cndmask_b32_e64 v146, v146, v147, s[34:35]
	s_mov_b64 exec, s[46:47]
	ds_write_b32 v229, v146
	s_mov_b64 exec, -1
	s_cmp_lg_u32 s48, 0
	s_cbranch_scc0 .Lap0_pass
	s_add_u32 s49, s49, 1
	s_cmp_lt_u32 s49, 2
	s_cbranch_scc1 .Lap0_pass
	s_branch .Lap0_s1end

; __device__ __forceinline__ float geluf_(float x) { return 0.5f * x * (1.0f + tanhf(0.7978845608028654f * (x + 0.044715f * x * x * x))); }
; __device__ __forceinline__ void ph_peer_apply(const Params& P, int layer, float* xlat, float* xctx_in, float* xctx_out, int nrows, bool write_next, char* smem, float* xlat_out = nullptr) {
;     ...
;     const float g0 = selg[(size_t)row * NSEL + lane], g1 = selg[(size_t)row * NSEL + 64 + lane];
;     ...
;     a0 = geluf_(a0) * g0; a1 = geluf_(a1) * g1;
.Lap0_s1end:
	s_waitcnt vmcnt(0) lgkmcnt(0)
	s_mov_b32 s14, 0
	s_mov_b32 s45, s13
.Lap0_gl_tok:
	s_cmp_ge_u32 s45, 0x8200
	s_cbranch_scc1 .Lap0_gl_done
	s_lshl_b32 s15, s45, 9
	s_add_u32 s24, s4, 0x1508c000
	s_addc_u32 s25, s5, 0
	s_add_u32 s24, s24, s15
	s_addc_u32 s25, s25, 0
	global_load_dword v40, v226, s[24:25]
	global_load_dword v41, v226, s[24:25] offset:256
	s_waitcnt vmcnt(0)
	s_lshl_b32 s15, s14, 9
	v_add_u32_e32 v194, s15, v228
	s_waitcnt lgkmcnt(0)
	ds_read_b32 v195, v194
	ds_read_b32 v196, v194 offset:256
	s_waitcnt lgkmcnt(0)
	v_mul_f32_e32 v199, v195, v195
	v_mul_f32_e32 v199, v199, v195
	v_fmamk_f32 v199, v199, 0x3d372713, v195
	v_mul_f32_e32 v199, 0xc0135761, v199
	v_exp_f32_e32 v199, v199
	s_nop 0
	v_add_f32_e32 v199, 1.0, v199
	v_rcp_f32_e32 v199, v199
	s_nop 0
	v_mul_f32_e32 v199, v199, v195
	v_mul_f32_e32 v197, v199, v40
	v_mul_f32_e32 v199, v196, v196
	v_mul_f32_e32 v199, v199, v196
	v_fmamk_f32 v199, v199, 0x3d372713, v196
	v_mul_f32_e32 v199, 0xc0135761, v199
	v_exp_f32_e32 v199, v199
	s_nop 0
	v_add_f32_e32 v199, 1.0, v199
	v_rcp_f32_e32 v199, v199
	s_nop 0
	v_mul_f32_e32 v199, v199, v196
	v_mul_f32_e32 v198, v199, v41
	ds_write_b32 v194, v197
	ds_write_b32 v194, v198 offset:256
	s_add_u32 s14, s14, 1
	s_add_u32 s45, s45, s44
	s_branch .Lap0_gl_tok
.Lap0_gl_done:
	s_waitcnt lgkmcnt(0)
	s_mov_b32 s14, 0
	s_mov_b32 s45, s13

; #define TIDX tid_fn()
; __device__ __forceinline__ void ph_peer_apply(const Params& P, int layer, float* xlat, float* xctx_in, float* xctx_out, int nrows, bool write_next, char* smem, float* xlat_out = nullptr) {
;     ...
;   const int tid = TIDX, wave = tid >> 6, lane = tid & 63;
;   const bool lact = lane < P6_NB;
;   const int lb = lact ? lane : 0;
;   for (int row = blockIdx.x * (NTHR / 64) + wave; row < nrows; row += gridDim.x * (NTHR / 64)) {
;     float xv[32];
; #pragma unroll
;     for (int j8 = 0; j8 < 4; ++j8) {
;       const h16x8 t = *(const h16x8*)(xq + (size_t)row * D + lb * 32 + j8 * 8);
; #pragma unroll
;       for (int j = 0; j < 8; ++j) xv[j8 * 8 + j] = lact ? (float)t[j] : 0.f;
;     }
;     const int id0 = seli[(size_t)row * NSEL + lane], id1 = seli[(size_t)row * NSEL + 64 + lane];
;     const float g0 = selg[(size_t)row * NSEL + lane], g1 = selg[(size_t)row * NSEL + 64 + lane];
;     float a0 = 0.f, a1 = 0.f;
;     P6Blk bufA[PB_G], bufB[PB_G];
.LBB0_3667:
	s_or_b64 exec, exec, s[2:3]
	s_waitcnt lgkmcnt(0)
	s_barrier
	s_load_dwordx4 s[4:7], s[96:97], 0x170
	s_load_dwordx4 s[8:11], s[96:97], 0x30
	v_readfirstlane_b32 s12, v0
	s_lshr_b32 s12, s12, 6
	v_and_b32_e32 v1, 63, v0
	v_mul_u32_u24_e32 v2, 24, v1
	v_add_u32_e32 v3, 0x600, v1
	v_lshlrev_b32_e32 v224, 6, v1
	v_lshlrev_b32_e32 v225, 7, v1
	v_lshlrev_b32_e32 v226, 2, v1
	v_lshrrev_b32_e32 v192, 2, v1
	v_and_b32_e32 v193, 1, v1
	v_lshl_add_u32 v192, v192, 1, v193
	v_lshlrev_b32_e32 v227, 2, v192
	s_mul_i32 s15, s12, 0x2800
	v_add_u32_e32 v228, s15, v226
	v_add_u32_e32 v227, s15, v227
	s_mov_b32 s46, 0x3333
	s_mov_b32 s47, 0
	s_mov_b32 s34, 0x22222222
	s_mov_b32 s35, 0x22222222
	s_waitcnt lgkmcnt(0)
	s_mov_b64 s[40:41], s[4:5]
	s_mov_b64 s[4:5], s[6:7]
	s_mov_b64 s[6:7], s[40:41]
	s_add_u32 s16, s4, 0x3c7c000
	s_addc_u32 s17, s5, 0
	s_add_u32 s18, s4, 0x7c7c000
	s_addc_u32 s19, s5, 0
	s_add_u32 s13, s60, s12
	s_lshl_b32 s44, s84, 3
	s_mov_b32 s50, 0
	s_mov_b32 s1, s13
.Lap1_ntl:
	s_add_u32 s50, s50, 1
	s_add_u32 s1, s1, s44
	s_cmp_lt_u32 s1, 0x8000
	s_cbranch_scc1 .Lap1_ntl
	s_mov_b32 s58, 0
	s_mov_b32 s59, 0
	s_mov_b32 s62, 0
	s_mov_b32 s48, 0
	s_mov_b32 s49, 0
	s_mov_b32 s45, s13
	s_lshl_b32 s15, s45, 12
	s_lshr_b32 s31, s45, 20
	s_add_u32 s20, s4, 0xbe4c000
	s_addc_u32 s21, s5, 0
	s_add_u32 s20, s20, s15
	s_addc_u32 s21, s21, s31
	s_lshl_b32 s15, s45, 9
	s_add_u32 s22, s4, 0x1404c000
	s_addc_u32 s23, s5, 0
	s_add_u32 s22, s22, s15
	s_addc_u32 s23, s23, 0
	global_load_dwordx4 v[4:7], v224, s[20:21]
	global_load_dwordx4 v[8:11], v224, s[20:21] offset:16
	global_load_dwordx4 v[12:15], v224, s[20:21] offset:32
	global_load_dwordx4 v[16:19], v224, s[20:21] offset:48
	global_load_dword v36, v226, s[22:23]
	global_load_dword v37, v226, s[22:23] offset:256
	s_waitcnt vmcnt(0)
	v_lshrrev_b32_e32 v195, 12, v36
	v_lshrrev_b32_e32 v196, 12, v37
	v_cmp_eq_u32_e64 s[52:53], s58, v195
	v_cmp_eq_u32_e64 s[54:55], s58, v196
	v_mov_b32_e32 v44, v36
	s_mov_b32 s61, 0
	s_mov_b32 s57, 0
	s_lshl_b32 s63, s59, 9
	s_mul_i32 s1, s12, 0x2800
	s_add_u32 s63, s63, s1
	s_lshl_b32 s1, s62, 31
	s_or_b32 s63, s63, s1
	v_mov_b32_e32 v45, 0

; __device__ __forceinline__ float geluf_(float x) { return 0.5f * x * (1.0f + tanhf(0.7978845608028654f * (x + 0.044715f * x * x * x))); }
; __device__ __forceinline__ void ph_peer_apply(const Params& P, int layer, float* xlat, float* xctx_in, float* xctx_out, int nrows, bool write_next, char* smem, float* xlat_out = nullptr) {
;     ...
;     const float g0 = selg[(size_t)row * NSEL + lane], g1 = selg[(size_t)row * NSEL + 64 + lane];
;     ...
;     a0 = geluf_(a0) * g0; a1 = geluf_(a1) * g1;
.Lap1_gl_tok:
	s_cmp_ge_u32 s45, 0x8000
	s_cbranch_scc1 .Lap1_gl_done
	s_lshl_b32 s15, s45, 9
	s_add_u32 s24, s4, 0x1508c000
	s_addc_u32 s25, s5, 0
	s_add_u32 s24, s24, s15
	s_addc_u32 s25, s25, 0
	global_load_dword v40, v226, s[24:25]
	global_load_dword v41, v226, s[24:25] offset:256
	s_waitcnt vmcnt(0)
	s_lshl_b32 s15, s14, 9
	v_add_u32_e32 v194, s15, v228
	s_waitcnt lgkmcnt(0)
	ds_read_b32 v195, v194
	ds_read_b32 v196, v194 offset:256
	s_waitcnt lgkmcnt(0)
	v_mul_f32_e32 v199, v195, v195
	v_mul_f32_e32 v199, v199, v195
	v_fmamk_f32 v199, v199, 0x3d372713, v195
	v_mul_f32_e32 v199, 0xc0135761, v199
	v_exp_f32_e32 v199, v199
	s_nop 0
	v_add_f32_e32 v199, 1.0, v199
	v_rcp_f32_e32 v199, v199
	s_nop 0
	v_mul_f32_e32 v199, v199, v195
	v_mul_f32_e32 v197, v199, v40
	v_mul_f32_e32 v199, v196, v196
	v_mul_f32_e32 v199, v199, v196
	v_fmamk_f32 v199, v199, 0x3d372713, v196
	v_mul_f32_e32 v199, 0xc0135761, v199
	v_exp_f32_e32 v199, v199
	s_nop 0
	v_add_f32_e32 v199, 1.0, v199
	v_rcp_f32_e32 v199, v199
	s_nop 0
	v_mul_f32_e32 v199, v199, v196
	v_mul_f32_e32 v198, v199, v41
	ds_write_b32 v194, v197
	ds_write_b32 v194, v198 offset:256
	s_add_u32 s14, s14, 1
	s_add_u32 s45, s45, s44
	s_branch .Lap1_gl_tok
